# GEMM phases: the workgroup barrier that follows the grid barrier moved down to just before the first tile DMA, so the waves that are waiting run the scalar prologue (and warm the instruction cache) be
# baseline (speedup 1.0000x reference)
; __device__ __forceinline__ void xcd_barrier(const XcdBarrier& b) {
;     ...
;     }
;     __syncthreads();
; __global__ void __launch_bounds__(512, 2) fwd_megakernel(Params p) {
;     ...
;     if (blockIdx.x == 0 && threadIdx.x == 0) __hip_atomic_store(barw + 16384 - 64, 0u, __ATOMIC_RELAXED, __HIP_MEMORY_SCOPE_AGENT);
.Lgb_done_0:
.LBB0_115:
	s_or_b64 exec, exec, s[0:1]
	s_waitcnt lgkmcnt(0)
	v_or_b32_e32 v0, s86, v152
	v_cmp_eq_u32_e32 vcc, 0, v0
	s_and_saveexec_b64 s[0:1], vcc
	s_cbranch_execz .LBB0_117
	v_mov_b32_e32 v0, 0
	global_store_dword v0, v0, s[26:27] sc1

;     __host__ __device__ bool next(int i, Unit& u) const {
;         const long L = (long)i * G + c; if (L >= nwg) return false;
;         int wgid = (int)L; { const int q = nwg / NXCD, r = nwg % NXCD, xcd = wgid % NXCD, off = wgid / NXCD; wgid = (xcd < r ? xcd * (q + 1) : r * (q + 1) + (xcd - r) * q) + off; }
;         const int nig = WGM * nN, gid = wgid / nig, fm = gid * WGM, gsz = (nM - fm) < WGM ? (nM - fm) : WGM;
; template <class Epi, class Sched, bool ALIGN_EPI = false, bool SP2 = false>
; __device__ __forceinline__ void gemm_phase(PG8_LAS unsigned char* lds, const Gemm g, const Sched& S, const Epi& E) {
;     const int tid = threadIdx.x, wid = __builtin_amdgcn_readfirstlane(tid >> 6), lane = tid & 63, wr = wid >> 2, wc = wid & 3, fr = lane & 15, fq = lane >> 4;
;     const int K = g.K, nt = K / BK;
;     unsigned voffA[2], voffB[2];
; #pragma unroll
;     for (int i = 0; i < 2; ++i) { int R, C; stage_rc(tid * 16 + i * 8192, R, C); const int Rb = Epi::PERM ? ((R & ~31) + perm32(R & 31)) : R;
;         voffA[i] = (unsigned)(R * K + C) * 2u; voffB[i] = (unsigned)(Rb * K + C) * 2u; }
;     const size_t kstep = (size_t)(BK * 2);
;     const size_t hstep = (size_t)HALF * K * 2;
;     const size_t tstep = 2 * hstep;
;     const unsigned ldsw = (unsigned)wid * 1024u;
;     const int aoff = lds_byte(wr * 64 + fr, fq * 8), boff = lds_byte(wc * 32 + fr, fq * 8);
;     ...
;     Unit cur, nxt; int ui = 0;
;     if (!S.next(0, cur)) return;
;     f32x4 acc[2][2][4][2];
; #pragma unroll
;     for (int a = 0; a < 2; ++a)
; #pragma unroll
;         for (int b = 0; b < 2; ++b)
; #pragma unroll
;             for (int m = 0; m < 4; ++m)
; #pragma unroll
;                 for (int n = 0; n < 2; ++n) acc[a][b][m][n] = (f32x4){0.f, 0.f, 0.f, 0.f};
;     bf16x8 At[4][2], B0[2][2], B1[2][2];
;     const char* cA = (const char*)g.A + (size_t)cur.pm * tstep; const char* cB = (const char*)g.Bt + (size_t)cur.pn * tstep;
;     S.a_ready(cur);
;     if constexpr (SP2) {
;         PG8_STAGE(PG8_SB(0, 0), cB, voffB); PG8_STAGE(PG8_SB(0, 1), cB + hstep, voffB); PG8_STAGE(PG8_SA(0, 0), cA, voffA); PG8_STAGE(PG8_SA(0, 1), cA + hstep, voffA);
;         if (wr == 1) PG8_BAR;
;         PG8_WAIT_V(2); PG8_BAR;
;         PG8_STAGE(PG8_SB(1, 0), cB + kstep, voffB); PG8_STAGE(PG8_SA(1, 0), cA + kstep, voffA); PG8_STAGE(PG8_SB(1, 1), cB + hstep + kstep, voffB);
;         PG8_WAIT_V(6); PG8_BAR;
.LBB0_123:
	v_readlane_b32 s0, v255, 5
	v_readlane_b32 s1, v255, 6
	s_and_b64 vcc, exec, s[0:1]
	v_readfirstlane_b32 s4, v152
	s_waitcnt lgkmcnt(0)
	s_cbranch_vccnz .LBB0_125
	s_ashr_i32 s0, s86, 31
	s_lshr_b32 s0, s0, 29
	s_add_i32 s0, s86, s0
	s_ashr_i32 s1, s0, 3
	s_and_b32 s0, s0, -8
	s_sub_i32 s0, s86, s0
	s_cmp_lt_i32 s0, 0
	s_movk_i32 s3, 0xb1
	s_cselect_b32 s3, s3, 0xb0
	s_mul_i32 s0, s0, s3
	s_add_i32 s0, s0, s1
	s_mul_hi_i32 s1, s0, 0x2e8ba2e9
	s_lshr_b32 s3, s1, 31
	s_ashr_i32 s1, s1, 5
	s_add_i32 s1, s1, s3
	s_lshl_b32 s3, s1, 3
	s_mulk_i32 s1, 0xb0
	s_sub_i32 s0, s0, s1
	s_sext_i32_i16 s1, s0
	s_bfe_u32 s1, s1, 0x3001c
	s_add_i32 s1, s0, s1
	s_sext_i32_i16 s5, s1
	s_and_b32 s1, s1, 0xfff8
	s_sub_i32 s0, s0, s1
	s_sext_i32_i16 s0, s0
	s_add_i32 s0, s3, s0
	s_ashr_i32 s6, s5, 3
.LBB0_125:
	v_lshlrev_b32_e32 v247, 4, v152
	v_and_b32_e32 v0, 32, v152
	v_bitop3_b32 v232, v247, v0, 48 bitop3:0x6c
	v_lshrrev_b32_e32 v0, 5, v152
	v_lshrrev_b32_e32 v2, 1, v152
	v_bfe_u32 v235, v152, 2, 4
	v_and_b32_e32 v0, 4, v0
	v_bfe_u32 v1, v152, 2, 2
	v_and_b32_e32 v236, 24, v2
	v_lshrrev_b32_e32 v246, 3, v152
	s_movk_i32 s1, 0x70
	v_or3_b32 v0, v0, v1, v236
	v_and_or_b32 v144, v246, s1, v235
	s_movk_i32 s1, 0x60
	v_add_u32_e32 v237, 0x2000, v247
	v_and_or_b32 v143, v246, s1, v0
	v_lshrrev_b32_e32 v1, 7, v237
	s_movk_i32 s1, 0xf0
	v_and_or_b32 v146, v1, s1, v235
	s_movk_i32 s1, 0xe0
	v_and_or_b32 v145, v1, s1, v0
	v_lshlrev_b32_e32 v0, 6, v152
	s_add_u32 s76, s72, 0xa800000
	v_and_b32_e32 v233, 64, v152
	v_and_b32_e32 v141, 0x3c0, v0
	v_lshlrev_b32_e32 v0, 2, v152
	s_addc_u32 s77, s73, 0
	v_readlane_b32 s8, v255, 5
	v_or_b32_e32 v140, v232, v233
	v_lshlrev_b32_e32 v254, 1, v236
	v_and_b32_e32 v142, 32, v0
	s_add_u32 s78, s72, 0x3000000
	v_readlane_b32 s9, v255, 6
	v_lshl_or_b32 v156, v144, 11, v140
	v_lshl_or_b32 v158, v143, 11, v140
	v_lshl_or_b32 v160, v146, 11, v140
	v_lshl_or_b32 v162, v145, 11, v140
	v_and_b32_e32 v234, 15, v152
	s_addc_u32 s79, s73, 0
	s_and_b64 vcc, exec, s[8:9]
	v_bitop3_b32 v231, v254, v142, v141 bitop3:0x36
	s_cbranch_vccz .Lhasunit_p1
	s_barrier
	s_branch .LBB0_173
.Lhasunit_p1:
	s_lshr_b32 s10, s4, 6
	s_ashr_i32 s1, s0, 31
	s_ashr_i32 s7, s6, 31
	s_lshr_b32 s5, s4, 8
	s_lshl_b32 s3, s10, 10
	s_lshl_b64 s[8:9], s[0:1], 19
	s_lshl_b64 s[12:13], s[6:7], 19
	s_add_u32 s36, s24, s12
	s_addc_u32 s37, s25, s13
	s_add_i32 s33, s3, 0
	s_add_i32 m0, s33, 0x10000
	v_mov_b32_e32 v159, 0
	s_barrier
	global_load_lds_dwordx4 v158, s[36:37]
	s_add_i32 m0, s33, 0x12000
	s_add_u32 s12, s36, 0x40000
	global_load_lds_dwordx4 v162, s[36:37]
	s_addc_u32 s13, s37, 0
	s_add_i32 m0, s33, 0x14000
	v_mov_b32_e32 v163, v159
	global_load_lds_dwordx4 v158, s[12:13]
	s_add_i32 m0, s33, 0x16000
	s_add_u32 s34, s76, s8
	s_addc_u32 s35, s77, s9
	s_add_i32 s40, s33, 0x2000
	global_load_lds_dwordx4 v162, s[12:13]
	s_mov_b32 m0, s33
	s_add_u32 s8, s34, 0x40000
	global_load_lds_dwordx4 v156, s[34:35]
	s_mov_b32 m0, s40
	s_addc_u32 s9, s35, 0
	s_add_i32 s41, s33, 0x4000
	global_load_lds_dwordx4 v160, s[34:35]
	s_mov_b32 m0, s41
	s_add_i32 s42, s33, 0x6000
	global_load_lds_dwordx4 v156, s[8:9]
	s_mov_b32 m0, s42
	v_mov_b32_e32 v157, v159
	global_load_lds_dwordx4 v160, s[8:9]
	s_movk_i32 s98, 0x100
	v_cmp_gt_u32_e32 vcc, s98, v152
	s_and_saveexec_b64 s[100:101], vcc
	s_cbranch_execz .Lrtab_p1
	v_lshl_or_b32 v188, s0, 8, v152
	v_ashrrev_i32_e32 v189, 31, v188
	v_lshlrev_b64 v[188:189], 6, v[188:189]
	v_lshl_add_u64 v[200:201], s[72:73], 0, v[188:189]
	global_load_dwordx4 v[188:191], v[200:201], off
	global_load_dwordx4 v[192:195], v[200:201], off offset:32
	global_load_dwordx4 v[196:199], v[200:201], off offset:16
	s_nop 0
	global_load_dwordx4 v[200:203], v[200:201], off offset:48
	v_mov_b32_e32 v206, 0x358637bd
	s_mov_b32 s98, 0xf800000
	s_waitcnt vmcnt(3)
	v_mov_b32_e32 v204, v188
	s_waitcnt vmcnt(2)
	v_mov_b32_e32 v205, v192
	v_mov_b32_e32 v192, v189
	v_mov_b32_e32 v188, v190
	v_mov_b32_e32 v189, v194
	v_mov_b32_e32 v194, v191
	s_waitcnt vmcnt(1)
	v_mov_b32_e32 v190, v196
	s_waitcnt vmcnt(0)
	v_mov_b32_e32 v191, v200
	v_mov_b32_e32 v200, v197
	v_mov_b32_e32 v196, v198
	v_mov_b32_e32 v197, v202
	v_mov_b32_e32 v202, v199
	v_pk_add_f32 v[192:193], v[204:205], v[192:193]
	v_pk_add_f32 v[188:189], v[188:189], v[194:195]
	v_pk_add_f32 v[190:191], v[190:191], v[200:201]
	v_pk_add_f32 v[194:195], v[196:197], v[202:203]
	v_pk_add_f32 v[188:189], v[192:193], v[188:189]
	v_pk_add_f32 v[190:191], v[190:191], v[194:195]
	s_nop 0
	v_pk_add_f32 v[188:189], v[188:189], v[190:191]
	v_mov_b32_e32 v190, 0x260
	v_add_f32_e32 v188, v188, v189
	v_fmac_f32_e32 v206, 0x3a800000, v188
	v_mul_f32_e32 v188, 0x4f800000, v206
	v_cmp_gt_f32_e32 vcc, s98, v206
	s_nop 1
	v_cndmask_b32_e32 v188, v206, v188, vcc
	v_sqrt_f32_e32 v189, v188
	s_nop 0
	v_add_u32_e32 v191, -1, v189
	v_add_u32_e32 v192, 1, v189
	v_fma_f32 v193, -v191, v189, v188
	v_fma_f32 v194, -v192, v189, v188
	v_cmp_ge_f32_e64 s[98:99], 0, v193
	s_nop 1
	v_cndmask_b32_e64 v189, v189, v191, s[98:99]
	v_cmp_lt_f32_e64 s[98:99], 0, v194
	s_nop 1
	v_cndmask_b32_e64 v189, v189, v192, s[98:99]
	v_mul_f32_e32 v191, 0x37800000, v189
	v_cndmask_b32_e32 v189, v189, v191, vcc
	v_cmp_class_f32_e32 vcc, v188, v190
	v_lshl_add_u32 v191, v152, 2, 0
	s_nop 0
	v_cndmask_b32_e32 v188, v189, v188, vcc
	v_div_scale_f32 v189, s[98:99], v188, v188, 1.0
	v_rcp_f32_e32 v190, v189
	v_div_scale_f32 v192, vcc, 1.0, v188, 1.0
	v_fma_f32 v193, -v189, v190, 1.0
	v_fmac_f32_e32 v190, v193, v190
	v_mul_f32_e32 v193, v192, v190
	v_fma_f32 v194, -v189, v193, v192
	v_fmac_f32_e32 v193, v194, v190
	v_fma_f32 v189, -v189, v193, v192
	v_div_fmas_f32 v189, v189, v190, v193
	v_div_fixup_f32 v188, v189, v188, 1.0
	v_add_u32_e32 v189, 0x20100, v191
	ds_write_b32 v189, v188

;     __host__ __device__ bool next(int i, Unit& u) const {
;         const long L = (long)i * G + c; if (L >= nwg) return false;
;         int wgid = (int)L; { const int q = nwg / NXCD, r = nwg % NXCD, xcd = wgid % NXCD, off = wgid / NXCD; wgid = (xcd < r ? xcd * (q + 1) : r * (q + 1) + (xcd - r) * q) + off; }
;         const int nig = WGM * nN, gid = wgid / nig, fm = gid * WGM, gsz = (nM - fm) < WGM ? (nM - fm) : WGM;
;         u.pm = fm + ((wgid % nig) % gsz); u.pn = (wgid % nig) / gsz; return true;
; __global__ void __launch_bounds__(512, 2) fwd_megakernel(Params p) {
;     ...
;     { pg8::Gemm g{HB, (const bf16*)(ws + WS_WD1), S, DM, DFF}; pg8::StaticOrder so; so.init(S, DM, G, (int)blockIdx.x);
;       pg8::EpiResid<true> E{nullptr, XB, SS1, 0.5f}; pg8::gemm_phase<pg8::EpiResid<true>, pg8::StaticOrder, true, true>(ldsl, g, so, E); }
.LBB0_349:
	s_or_b64 exec, exec, s[0:1]
	s_cmpk_lt_i32 s86, 0x100
	v_lshrrev_b32_e32 v175, 2, v152
	s_cselect_b64 s[0:1], -1, 0
	s_cmpk_gt_i32 s86, 0xff
	v_readfirstlane_b32 s8, v152
	s_waitcnt lgkmcnt(0)
	s_cbranch_scc1 .LBB0_355
	s_ashr_i32 s2, s86, 31
	s_lshr_b32 s2, s2, 29
	s_add_i32 s2, s86, s2
	s_and_b32 s3, s2, -8
	s_sub_i32 s3, s86, s3
	s_cmp_gt_i32 s3, -1
	s_cbranch_scc0 .LBB0_352
	s_lshl_b32 s6, s3, 5
	s_cbranch_execz .LBB0_353
	s_branch .LBB0_354

; #define PG8_STAGE(bufoff, gbase, voff) do { _Pragma("unroll") for (int _i = 0; _i < 2; ++_i) \
;         __builtin_amdgcn_global_load_lds((const unsigned*)((const char*)(gbase) + (voff)[_i]), (PG8_LAS unsigned*)(lds + (bufoff) + ldsw + _i * 8192), 16, 0, 0); } while (0)
; #define PG8_WAIT_V(n) asm volatile("s_waitcnt vmcnt(" #n ")" ::: "memory")
; #define PG8_BAR __builtin_amdgcn_s_barrier()
; template <class Epi, class Sched, bool ALIGN_EPI = false, bool SP2 = false>
; __device__ __forceinline__ void gemm_phase(PG8_LAS unsigned char* lds, const Gemm g, const Sched& S, const Epi& E) {
;     ...
;     for (int i = 0; i < 2; ++i) { int R, C; stage_rc(tid * 16 + i * 8192, R, C); const int Rb = Epi::PERM ? ((R & ~31) + perm32(R & 31)) : R;
;         voffA[i] = (unsigned)(R * K + C) * 2u; voffB[i] = (unsigned)(Rb * K + C) * 2u; }
;     const size_t kstep = (size_t)(BK * 2);
;     const size_t hstep = (size_t)HALF * K * 2;
;     const size_t tstep = 2 * hstep;
;     const unsigned ldsw = (unsigned)wid * 1024u;
;     const int aoff = lds_byte(wr * 64 + fr, fq * 8), boff = lds_byte(wc * 32 + fr, fq * 8);
;     ...
;     Unit cur, nxt; int ui = 0;
;     if (!S.next(0, cur)) return;
;     f32x4 acc[2][2][4][2];
; #pragma unroll
;     for (int a = 0; a < 2; ++a)
; #pragma unroll
;         for (int b = 0; b < 2; ++b)
; #pragma unroll
;             for (int m = 0; m < 4; ++m)
; #pragma unroll
;                 for (int n = 0; n < 2; ++n) acc[a][b][m][n] = (f32x4){0.f, 0.f, 0.f, 0.f};
;     bf16x8 At[4][2], B0[2][2], B1[2][2];
;     const char* cA = (const char*)g.A + (size_t)cur.pm * tstep; const char* cB = (const char*)g.Bt + (size_t)cur.pn * tstep;
;     S.a_ready(cur);
;     if constexpr (SP2) {
;         PG8_STAGE(PG8_SB(0, 0), cB, voffB); PG8_STAGE(PG8_SB(0, 1), cB + hstep, voffB); PG8_STAGE(PG8_SA(0, 0), cA, voffA); PG8_STAGE(PG8_SA(0, 1), cA + hstep, voffA);
;         if (wr == 1) PG8_BAR;
;         PG8_WAIT_V(2); PG8_BAR;
;         PG8_STAGE(PG8_SB(1, 0), cB + kstep, voffB); PG8_STAGE(PG8_SA(1, 0), cA + kstep, voffA); PG8_STAGE(PG8_SB(1, 1), cB + hstep + kstep, voffB);
;         PG8_WAIT_V(6); PG8_BAR;
.LBB0_355:
	v_lshrrev_b32_e32 v0, 1, v140
	v_mul_u32_u24_e32 v241, 0xb00, v144
	v_or_b32_e32 v1, v0, v241
	v_lshlrev_b32_e32 v164, 1, v1
	v_mul_u32_u24_e32 v1, 0xb00, v143
	v_or_b32_e32 v1, v1, v0
	v_mul_u32_u24_e32 v242, 0xb00, v146
	v_lshlrev_b32_e32 v166, 1, v1
	v_or_b32_e32 v1, v242, v0
	v_lshlrev_b32_e32 v168, 1, v1
	v_mul_u32_u24_e32 v1, 0xb00, v145
	v_or_b32_e32 v0, v1, v0
	v_lshlrev_b32_e32 v170, 1, v0
	v_cndmask_b32_e64 v0, 0, 1, s[0:1]
	v_bfe_u32 v243, v152, 4, 2
	v_cmp_ne_u32_e64 s[2:3], 1, v0
	v_lshlrev_b32_e32 v172, 4, v243
	s_add_u32 s14, s72, 0x100000
	v_writelane_b32 v255, s2, 12
	v_lshlrev_b32_e32 v244, 3, v243
	s_addc_u32 s15, s73, 0
	v_writelane_b32 v255, s3, 13
	s_andn2_b64 vcc, exec, s[0:1]
	v_bitop3_b32 v245, v172, v142, v141 bitop3:0x36
	s_cbranch_vccz .Lhasunit_p2
	s_barrier
	s_branch .LBB0_395
.Lhasunit_p2:
	s_add_u32 s2, s72, 0x1100000
	s_addc_u32 s3, s73, 0
	s_lshr_b32 s1, s8, 6
	s_lshr_b32 s0, s8, 8
	s_lshl_b32 s28, s1, 10
	s_mul_i32 s7, s4, 0x160000
	s_mul_hi_i32 s6, s4, 0x160000
	s_add_u32 s24, s2, s7
	s_addc_u32 s25, s3, s6
	s_add_i32 s29, s28, 0
	s_add_i32 m0, s29, 0x10000
	s_mul_i32 s9, s45, 0x160000
	s_barrier
	global_load_lds_dwordx4 v166, s[24:25]
	s_add_i32 m0, s29, 0x12000
	s_add_u32 s6, s24, 0xb0000
	global_load_lds_dwordx4 v170, s[24:25]
	s_addc_u32 s7, s25, 0
	s_add_i32 m0, s29, 0x14000
	s_mul_hi_i32 s5, s45, 0x160000
	global_load_lds_dwordx4 v166, s[6:7]
	s_add_i32 m0, s29, 0x16000
	s_add_u32 s20, s78, s9
	s_addc_u32 s21, s79, s5
	s_add_i32 s30, s29, 0x2000
	global_load_lds_dwordx4 v170, s[6:7]
	s_mov_b32 m0, s29
	s_add_u32 s6, s20, 0xb0000
	global_load_lds_dwordx4 v164, s[20:21]
	s_mov_b32 m0, s30
	s_addc_u32 s7, s21, 0
	s_add_i32 s31, s29, 0x4000
	global_load_lds_dwordx4 v168, s[20:21]
	s_mov_b32 m0, s31
	s_add_i32 s33, s29, 0x6000
	global_load_lds_dwordx4 v164, s[6:7]
	s_mov_b32 m0, s33
	v_mov_b32_e32 v167, 0
	global_load_lds_dwordx4 v168, s[6:7]
	v_mov_b32_e32 v171, v167
	v_mov_b32_e32 v165, v167
	v_mov_b32_e32 v169, v167
	s_cmp_eq_u32 s0, 1
	s_mov_b32 s5, 0
	v_lshl_add_u64 v[6:7], s[24:25], 0, v[166:167]
	v_lshl_add_u64 v[4:5], s[24:25], 0, v[170:171]
	v_lshl_add_u64 v[0:1], s[20:21], 0, v[164:165]
	s_cselect_b64 s[6:7], -1, 0
	s_cmp_lg_u32 s0, 1
	v_lshl_add_u64 v[2:3], s[20:21], 0, v[168:169]
	s_cbranch_scc1 .LBB0_358
	s_barrier

; #define LAS __attribute__((address_space(3)))
;     __host__ __device__ bool next(int i, Unit& u) const {
;         const long L = (long)i * G + c; if (L >= nwg) return false;
;         int wgid = (int)L; { const int q = nwg / NXCD, r = nwg % NXCD, xcd = wgid % NXCD, off = wgid / NXCD; wgid = (xcd < r ? xcd * (q + 1) : r * (q + 1) + (xcd - r) * q) + off; }
;         const int nig = WGM * nN, gid = wgid / nig, fm = gid * WGM, gsz = (nM - fm) < WGM ? (nM - fm) : WGM;
;         u.pm = fm + ((wgid % nig) % gsz); u.pn = (wgid % nig) / gsz; return true;
; __device__ __forceinline__ int fill_rtab(const pg8::StaticOrder& so, const float* ss, LAS float* rtab) {
;     pg8::Unit u0; int pm0 = -1;
;     if (so.next(0, u0)) { pm0 = u0.pm; if (threadIdx.x < 256) rtab[threadIdx.x] = pg8::row_rstd(ss, pm0 * 256 + (int)threadIdx.x); }
;     __syncthreads();
;     return pm0;
; }
.Lgb_done_2:
.LBB0_447:
	s_or_b64 exec, exec, s[0:1]
	s_cmpk_lt_i32 s86, 0x2c0
	v_lshrrev_b32_e32 v165, 4, v152
	s_cselect_b64 s[4:5], -1, 0
	s_cmpk_gt_i32 s86, 0x2bf
	s_waitcnt lgkmcnt(0)
	s_cbranch_scc1 .LBB0_449
	s_ashr_i32 s0, s86, 31
	s_lshr_b32 s0, s0, 29
	s_add_i32 s0, s86, s0
	s_ashr_i32 s1, s0, 3
	s_and_b32 s0, s0, -8
	s_sub_i32 s0, s86, s0
	s_cmp_lt_i32 s0, 0
	s_movk_i32 s2, 0x59
	s_cselect_b32 s2, s2, 0x58
	s_mul_i32 s0, s0, s2
	s_add_i32 s0, s0, s1
	s_mul_hi_i32 s1, s0, 0x2e8ba2e9
	s_lshr_b32 s2, s1, 31
	s_ashr_i32 s1, s1, 4
	s_add_i32 s1, s1, s2
	s_lshl_b32 s2, s1, 3
	s_mulk_i32 s1, 0x58
	s_sub_i32 s0, s0, s1
	s_bfe_i32 s1, s0, 0x80000
	s_bfe_u32 s1, s1, 0x3000c
	s_add_i32 s1, s0, s1
	s_and_b32 s1, s1, 0xf8
	s_sub_i32 s0, s0, s1
	s_sext_i32_i8 s0, s0
	s_add_i32 s3, s2, s0

; __device__ __forceinline__ float row_rstd(const float* ss, int row) {
;     const f32x4* p = (const f32x4*)(ss + (size_t)row * 16);
;     const f32x4 a = p[0], b = p[1], c = p[2], d = p[3];
;     const float s = (((a[0] + a[1]) + (a[2] + a[3])) + ((b[0] + b[1]) + (b[2] + b[3]))) + (((c[0] + c[1]) + (c[2] + c[3])) + ((d[0] + d[1]) + (d[2] + d[3])));
;     return 1.0f / sqrtf(s * (1.0f / 1024.0f) + 1e-6f);
; }
; template <class Epi, class Sched, bool ALIGN_EPI = false, bool SP2 = false>
; __device__ __forceinline__ void gemm_phase(PG8_LAS unsigned char* lds, const Gemm g, const Sched& S, const Epi& E) {
;     const int tid = threadIdx.x, wid = __builtin_amdgcn_readfirstlane(tid >> 6), lane = tid & 63, wr = wid >> 2, wc = wid & 3, fr = lane & 15, fq = lane >> 4;
;     const int K = g.K, nt = K / BK;
;     unsigned voffA[2], voffB[2];
; #pragma unroll
;     for (int i = 0; i < 2; ++i) { int R, C; stage_rc(tid * 16 + i * 8192, R, C); const int Rb = Epi::PERM ? ((R & ~31) + perm32(R & 31)) : R;
;         voffA[i] = (unsigned)(R * K + C) * 2u; voffB[i] = (unsigned)(Rb * K + C) * 2u; }
;     const size_t kstep = (size_t)(BK * 2);
;     const size_t hstep = (size_t)HALF * K * 2;
;     const size_t tstep = 2 * hstep;
;     const unsigned ldsw = (unsigned)wid * 1024u;
;     const int aoff = lds_byte(wr * 64 + fr, fq * 8), boff = lds_byte(wc * 32 + fr, fq * 8);
;     ...
;     Unit cur, nxt; int ui = 0;
;     if (!S.next(0, cur)) return;
;     f32x4 acc[2][2][4][2];
; #pragma unroll
;     for (int a = 0; a < 2; ++a)
; #pragma unroll
;         for (int b = 0; b < 2; ++b)
; #pragma unroll
;             for (int m = 0; m < 4; ++m)
; #pragma unroll
;                 for (int n = 0; n < 2; ++n) acc[a][b][m][n] = (f32x4){0.f, 0.f, 0.f, 0.f};
;     bf16x8 At[4][2], B0[2][2], B1[2][2];
;     const char* cA = (const char*)g.A + (size_t)cur.pm * tstep; const char* cB = (const char*)g.Bt + (size_t)cur.pn * tstep;
;     S.a_ready(cur);
;     if constexpr (SP2) {
;         PG8_STAGE(PG8_SB(0, 0), cB, voffB); PG8_STAGE(PG8_SB(0, 1), cB + hstep, voffB); PG8_STAGE(PG8_SA(0, 0), cA, voffA); PG8_STAGE(PG8_SA(0, 1), cA + hstep, voffA);
;         if (wr == 1) PG8_BAR;
;         PG8_WAIT_V(2); PG8_BAR;
;         PG8_STAGE(PG8_SB(1, 0), cB + kstep, voffB); PG8_STAGE(PG8_SA(1, 0), cA + kstep, voffA); PG8_STAGE(PG8_SB(1, 1), cB + hstep + kstep, voffB);
;         PG8_WAIT_V(6); PG8_BAR;
.LBB0_453:
	s_and_b64 vcc, exec, s[0:1]
	v_readfirstlane_b32 s8, v152
	s_waitcnt lgkmcnt(0)
	s_cbranch_vccnz .LBB0_455
	s_ashr_i32 s3, s86, 31
	s_lshr_b32 s3, s3, 29
	s_add_i32 s3, s86, s3
	s_ashr_i32 s4, s3, 3
	s_and_b32 s3, s3, -8
	s_sub_i32 s3, s86, s3
	s_cmp_lt_i32 s3, 0
	s_movk_i32 s5, 0x59
	s_cselect_b32 s5, s5, 0x58
	s_mul_i32 s3, s3, s5
	s_add_i32 s3, s3, s4
	s_mul_hi_i32 s4, s3, 0x2e8ba2e9
	s_lshr_b32 s5, s4, 31
	s_ashr_i32 s4, s4, 4
	s_add_i32 s4, s4, s5
	s_lshl_b32 s5, s4, 3
	s_mulk_i32 s4, 0x58
	s_sub_i32 s3, s3, s4
	s_bfe_i32 s4, s3, 0x80000
	s_bfe_u32 s4, s4, 0x3000c
	s_add_i32 s4, s3, s4
	s_bfe_i32 s6, s4, 0x80000
	s_and_b32 s4, s4, 0xf8
	s_sub_i32 s3, s3, s4
	s_sext_i32_i16 s6, s6
	s_sext_i32_i8 s3, s3
	s_add_i32 s12, s5, s3
	s_ashr_i32 s28, s6, 3
.LBB0_455:
	s_add_u32 s54, s72, 0x400000
	s_addc_u32 s55, s73, 0
	s_and_b64 vcc, exec, s[0:1]
	s_cbranch_vccz .Lhasunit_p3
	s_barrier
	s_branch .LBB0_541
.Lhasunit_p3:
	s_lshr_b32 s6, s8, 6
	s_lshr_b32 s9, s8, 8
	s_lshl_b32 s3, s6, 10
	s_add_u32 s33, s72, 0x2800000
	s_addc_u32 s36, s73, 0
	s_ashr_i32 s13, s12, 31
	s_ashr_i32 s29, s28, 31
	s_lshl_b64 s[0:1], s[12:13], 19
	s_lshl_b64 s[4:5], s[28:29], 19
	s_add_u32 s30, s33, s4
	s_addc_u32 s31, s36, s5
	s_add_i32 s29, s3, 0
	s_add_i32 m0, s29, 0x10000
	v_mov_b32_e32 v159, 0
	s_barrier
	global_load_lds_dwordx4 v158, s[30:31]
	s_add_i32 m0, s29, 0x12000
	s_add_u32 s4, s30, 0x40000
	global_load_lds_dwordx4 v162, s[30:31]
	s_addc_u32 s5, s31, 0
	s_add_i32 m0, s29, 0x14000
	v_mov_b32_e32 v163, v159
	global_load_lds_dwordx4 v158, s[4:5]
	s_add_i32 m0, s29, 0x16000
	s_add_u32 s0, s76, s0
	s_addc_u32 s1, s77, s1
	s_add_i32 s37, s29, 0x2000
	global_load_lds_dwordx4 v162, s[4:5]
	s_mov_b32 m0, s29
	s_add_u32 s4, s0, 0x40000
	global_load_lds_dwordx4 v156, s[0:1]
	s_mov_b32 m0, s37
	s_addc_u32 s5, s1, 0
	s_add_i32 s38, s29, 0x4000
	global_load_lds_dwordx4 v160, s[0:1]
	s_mov_b32 m0, s38
	s_add_i32 s39, s29, 0x6000
	global_load_lds_dwordx4 v156, s[4:5]
	s_mov_b32 m0, s39
	v_mov_b32_e32 v157, v159
	global_load_lds_dwordx4 v160, s[4:5]
	s_movk_i32 s98, 0x100
	v_cmp_gt_u32_e32 vcc, s98, v152
	s_and_saveexec_b64 s[100:101], vcc
	s_cbranch_execz .Lrtab_p3
	v_lshl_or_b32 v188, s12, 8, v152
	v_ashrrev_i32_e32 v189, 31, v188
	v_lshlrev_b64 v[188:189], 6, v[188:189]
	v_lshl_add_u64 v[200:201], s[14:15], 0, v[188:189]
	global_load_dwordx4 v[188:191], v[200:201], off
	global_load_dwordx4 v[192:195], v[200:201], off offset:32
	global_load_dwordx4 v[196:199], v[200:201], off offset:16
	s_nop 0
	global_load_dwordx4 v[200:203], v[200:201], off offset:48
	v_mov_b32_e32 v206, 0x358637bd
	s_mov_b32 s98, 0xf800000
	s_waitcnt vmcnt(3)
	v_mov_b32_e32 v204, v188
	s_waitcnt vmcnt(2)
	v_mov_b32_e32 v205, v192
	v_mov_b32_e32 v192, v189
	v_mov_b32_e32 v188, v190
	v_mov_b32_e32 v189, v194
	v_mov_b32_e32 v194, v191
	s_waitcnt vmcnt(1)
	v_mov_b32_e32 v190, v196
	s_waitcnt vmcnt(0)
	v_mov_b32_e32 v191, v200
	v_mov_b32_e32 v200, v197
	v_mov_b32_e32 v196, v198
	v_mov_b32_e32 v197, v202
	v_mov_b32_e32 v202, v199
	v_pk_add_f32 v[192:193], v[204:205], v[192:193]
	v_pk_add_f32 v[188:189], v[188:189], v[194:195]
	v_pk_add_f32 v[190:191], v[190:191], v[200:201]
	v_pk_add_f32 v[194:195], v[196:197], v[202:203]
	v_pk_add_f32 v[188:189], v[192:193], v[188:189]
	v_pk_add_f32 v[190:191], v[190:191], v[194:195]
	s_nop 0
	v_pk_add_f32 v[188:189], v[188:189], v[190:191]
	v_mov_b32_e32 v190, 0x260
	v_add_f32_e32 v188, v188, v189
	v_fmac_f32_e32 v206, 0x3a800000, v188
	v_mul_f32_e32 v188, 0x4f800000, v206
	v_cmp_gt_f32_e32 vcc, s98, v206
	s_nop 1
	v_cndmask_b32_e32 v188, v206, v188, vcc
	v_sqrt_f32_e32 v189, v188
	s_nop 0
	v_add_u32_e32 v191, -1, v189
	v_add_u32_e32 v192, 1, v189
	v_fma_f32 v193, -v191, v189, v188
	v_fma_f32 v194, -v192, v189, v188
	v_cmp_ge_f32_e64 s[98:99], 0, v193
	s_nop 1
	v_cndmask_b32_e64 v189, v189, v191, s[98:99]
	v_cmp_lt_f32_e64 s[98:99], 0, v194
	s_nop 1
	v_cndmask_b32_e64 v189, v189, v192, s[98:99]
	v_mul_f32_e32 v191, 0x37800000, v189
	v_cndmask_b32_e32 v189, v189, v191, vcc
	v_cmp_class_f32_e32 vcc, v188, v190
	v_lshl_add_u32 v191, v152, 2, 0
	s_nop 0
	v_cndmask_b32_e32 v188, v189, v188, vcc
	v_div_scale_f32 v189, s[98:99], v188, v188, 1.0
	v_rcp_f32_e32 v190, v189
	v_div_scale_f32 v192, vcc, 1.0, v188, 1.0
	v_fma_f32 v193, -v189, v190, 1.0
	v_fmac_f32_e32 v190, v193, v190
	v_mul_f32_e32 v193, v192, v190
	v_fma_f32 v194, -v189, v193, v192
	v_fmac_f32_e32 v193, v194, v190
	v_fma_f32 v189, -v189, v193, v192
	v_div_fmas_f32 v189, v189, v190, v193
	v_div_fixup_f32 v188, v189, v188, 1.0
	v_add_u32_e32 v189, 0x20100, v191
	ds_write_b32 v189, v188

;     __host__ __device__ bool next(int i, Unit& u) const {
;         const long L = (long)i * G + c; if (L >= nwg) return false;
;         int wgid = (int)L; { const int q = nwg / NXCD, r = nwg % NXCD, xcd = wgid % NXCD, off = wgid / NXCD; wgid = (xcd < r ? xcd * (q + 1) : r * (q + 1) + (xcd - r) * q) + off; }
;         const int nig = WGM * nN, gid = wgid / nig, fm = gid * WGM, gsz = (nM - fm) < WGM ? (nM - fm) : WGM;
;         u.pm = fm + ((wgid % nig) % gsz); u.pn = (wgid % nig) / gsz; return true;
; __global__ void __launch_bounds__(512, 2) fwd_megakernel(Params p) {
;     ...
;     { pg8::Gemm g{MIX, (const bf16*)(ws + WS_WOUT), S, DM, DM}; pg8::StaticOrder so; so.init(S, DM, G, (int)blockIdx.x);
;       pg8::EpiResid<true> E{nullptr, XB, SS2, 1.0f}; pg8::gemm_phase<pg8::EpiResid<true>, pg8::StaticOrder, true, true>(ldsl, g, so, E); }
.Lgb_done_6:
.LBB0_1211:
	s_or_b64 exec, exec, s[0:1]
	v_readlane_b32 s0, v255, 12
	v_readlane_b32 s1, v255, 13
	s_and_b64 vcc, exec, s[0:1]
	v_readfirstlane_b32 s8, v152
	s_waitcnt lgkmcnt(0)
	s_cbranch_vccnz .LBB0_1217
	s_ashr_i32 s0, s86, 31
	s_lshr_b32 s0, s0, 29
	s_add_i32 s2, s86, s0
	s_and_b32 s0, s2, -8
	s_sub_i32 s3, s86, s0
	s_cmp_gt_i32 s3, -1
	s_cbranch_scc0 .LBB0_1214
	s_lshl_b32 s4, s3, 5
	s_cbranch_execz .LBB0_1215
	s_branch .LBB0_1216

; #define PG8_STAGE(bufoff, gbase, voff) do { _Pragma("unroll") for (int _i = 0; _i < 2; ++_i) \
;         __builtin_amdgcn_global_load_lds((const unsigned*)((const char*)(gbase) + (voff)[_i]), (PG8_LAS unsigned*)(lds + (bufoff) + ldsw + _i * 8192), 16, 0, 0); } while (0)
; #define PG8_WAIT_V(n) asm volatile("s_waitcnt vmcnt(" #n ")" ::: "memory")
; #define PG8_BAR __builtin_amdgcn_s_barrier()
; template <class Epi, class Sched, bool ALIGN_EPI = false, bool SP2 = false>
; __device__ __forceinline__ void gemm_phase(PG8_LAS unsigned char* lds, const Gemm g, const Sched& S, const Epi& E) {
;     ...
;     for (int i = 0; i < 2; ++i) { int R, C; stage_rc(tid * 16 + i * 8192, R, C); const int Rb = Epi::PERM ? ((R & ~31) + perm32(R & 31)) : R;
;         voffA[i] = (unsigned)(R * K + C) * 2u; voffB[i] = (unsigned)(Rb * K + C) * 2u; }
;     const size_t kstep = (size_t)(BK * 2);
;     const size_t hstep = (size_t)HALF * K * 2;
;     const size_t tstep = 2 * hstep;
;     const unsigned ldsw = (unsigned)wid * 1024u;
;     const int aoff = lds_byte(wr * 64 + fr, fq * 8), boff = lds_byte(wc * 32 + fr, fq * 8);
;     ...
;     Unit cur, nxt; int ui = 0;
;     if (!S.next(0, cur)) return;
;     f32x4 acc[2][2][4][2];
; #pragma unroll
;     for (int a = 0; a < 2; ++a)
; #pragma unroll
;         for (int b = 0; b < 2; ++b)
; #pragma unroll
;             for (int m = 0; m < 4; ++m)
; #pragma unroll
;                 for (int n = 0; n < 2; ++n) acc[a][b][m][n] = (f32x4){0.f, 0.f, 0.f, 0.f};
;     bf16x8 At[4][2], B0[2][2], B1[2][2];
;     const char* cA = (const char*)g.A + (size_t)cur.pm * tstep; const char* cB = (const char*)g.Bt + (size_t)cur.pn * tstep;
;     S.a_ready(cur);
;     if constexpr (SP2) {
;         PG8_STAGE(PG8_SB(0, 0), cB, voffB); PG8_STAGE(PG8_SB(0, 1), cB + hstep, voffB); PG8_STAGE(PG8_SA(0, 0), cA, voffA); PG8_STAGE(PG8_SA(0, 1), cA + hstep, voffA);
;         if (wr == 1) PG8_BAR;
;         PG8_WAIT_V(2); PG8_BAR;
;         PG8_STAGE(PG8_SB(1, 0), cB + kstep, voffB); PG8_STAGE(PG8_SA(1, 0), cA + kstep, voffA); PG8_STAGE(PG8_SB(1, 1), cB + hstep + kstep, voffB);
;         PG8_WAIT_V(6); PG8_BAR;
.LBB0_1217:
	v_readlane_b32 s2, v255, 12
	s_add_u32 s12, s72, 0x200000
	v_readlane_b32 s3, v255, 13
	s_addc_u32 s13, s73, 0
	s_and_b64 vcc, exec, s[2:3]
	s_cbranch_vccz .Lhasunit_p7
	s_barrier
	s_branch .LBB0_1253
.Lhasunit_p7:
	s_add_u32 s2, s72, 0x2e00000
	s_addc_u32 s3, s73, 0
	s_lshr_b32 s6, s8, 6
	s_ashr_i32 s25, s24, 31
	s_ashr_i32 s1, s0, 31
	s_lshr_b32 s9, s8, 8
	s_lshl_b32 s33, s6, 10
	s_lshl_b64 s[4:5], s[24:25], 19
	s_lshl_b64 s[10:11], s[0:1], 19
	s_add_u32 s28, s2, s10
	s_addc_u32 s29, s3, s11
	s_add_i32 s34, s33, 0
	s_add_i32 m0, s34, 0x10000
	v_mov_b32_e32 v159, 0
	s_barrier
	global_load_lds_dwordx4 v158, s[28:29]
	s_add_i32 m0, s34, 0x12000
	s_add_u32 s10, s28, 0x40000
	global_load_lds_dwordx4 v162, s[28:29]
	s_addc_u32 s11, s29, 0
	s_add_i32 m0, s34, 0x14000
	v_mov_b32_e32 v163, v159
	global_load_lds_dwordx4 v158, s[10:11]
	s_add_i32 m0, s34, 0x16000
	s_add_u32 s26, s48, s4
	s_addc_u32 s27, s49, s5
	s_add_i32 s35, s34, 0x2000
	global_load_lds_dwordx4 v162, s[10:11]
	s_mov_b32 m0, s34
	s_add_u32 s4, s26, 0x40000
	global_load_lds_dwordx4 v156, s[26:27]
	s_mov_b32 m0, s35
	s_addc_u32 s5, s27, 0
	s_add_i32 s36, s34, 0x4000
	global_load_lds_dwordx4 v160, s[26:27]
	s_mov_b32 m0, s36
	s_add_i32 s37, s34, 0x6000
	global_load_lds_dwordx4 v156, s[4:5]
	s_mov_b32 m0, s37
	v_mov_b32_e32 v157, v159
	global_load_lds_dwordx4 v160, s[4:5]
	v_mov_b32_e32 v161, v159
	s_cmp_eq_u32 s9, 1
	s_mov_b32 s1, 0
	s_waitcnt vmcnt(0)
	v_lshl_add_u64 v[6:7], s[28:29], 0, v[158:159]
	v_lshl_add_u64 v[4:5], s[28:29], 0, v[162:163]
	v_lshl_add_u64 v[0:1], s[26:27], 0, v[156:157]
	s_cselect_b64 s[4:5], -1, 0
	s_cmp_lg_u32 s9, 1
	v_lshl_add_u64 v[2:3], s[26:27], 0, v[160:161]
	s_cbranch_scc1 .LBB0_1220
	s_barrier

; #define LAS __attribute__((address_space(3)))
;     __host__ __device__ bool next(int i, Unit& u) const {
;         const long L = (long)i * G + c; if (L >= nwg) return false;
;         int wgid = (int)L; { const int q = nwg / NXCD, r = nwg % NXCD, xcd = wgid % NXCD, off = wgid / NXCD; wgid = (xcd < r ? xcd * (q + 1) : r * (q + 1) + (xcd - r) * q) + off; }
;         const int nig = WGM * nN, gid = wgid / nig, fm = gid * WGM, gsz = (nM - fm) < WGM ? (nM - fm) : WGM;
;         u.pm = fm + ((wgid % nig) % gsz); u.pn = (wgid % nig) / gsz; return true;
; __device__ __forceinline__ int fill_rtab(const pg8::StaticOrder& so, const float* ss, LAS float* rtab) {
;     pg8::Unit u0; int pm0 = -1;
;     if (so.next(0, u0)) { pm0 = u0.pm; if (threadIdx.x < 256) rtab[threadIdx.x] = pg8::row_rstd(ss, pm0 * 256 + (int)threadIdx.x); }
;     __syncthreads();
;     return pm0;
; }
.Lgb_done_7:
.LBB0_1305:
	s_or_b64 exec, exec, s[0:1]
	s_and_b64 vcc, exec, s[48:49]
	s_waitcnt lgkmcnt(0)
	s_cbranch_vccnz .LBB0_1307
	s_ashr_i32 s0, s86, 31
	s_lshr_b32 s0, s0, 29
	s_add_i32 s0, s86, s0
	s_ashr_i32 s1, s0, 3
	s_and_b32 s0, s0, -8
	s_sub_i32 s0, s86, s0
	s_cmp_lt_i32 s0, 0
	s_movk_i32 s2, 0xb1
	s_cselect_b32 s2, s2, 0xb0
	s_mul_i32 s0, s0, s2
	s_add_i32 s0, s0, s1
	s_mul_hi_i32 s1, s0, 0x2e8ba2e9
	s_lshr_b32 s2, s1, 31
	s_ashr_i32 s1, s1, 5
	s_add_i32 s1, s1, s2
	s_lshl_b32 s2, s1, 3
	s_mulk_i32 s1, 0xb0
	s_sub_i32 s0, s0, s1
	s_bfe_u32 s1, s0, 0x3001c
	s_add_i32 s1, s0, s1
	s_and_b32 s1, s1, 0xfff8
	s_sub_i32 s0, s0, s1
	s_sext_i32_i16 s0, s0
	s_add_i32 s3, s2, s0

; __device__ __forceinline__ float row_rstd(const float* ss, int row) {
;     const f32x4* p = (const f32x4*)(ss + (size_t)row * 16);
;     const f32x4 a = p[0], b = p[1], c = p[2], d = p[3];
;     const float s = (((a[0] + a[1]) + (a[2] + a[3])) + ((b[0] + b[1]) + (b[2] + b[3]))) + (((c[0] + c[1]) + (c[2] + c[3])) + ((d[0] + d[1]) + (d[2] + d[3])));
;     return 1.0f / sqrtf(s * (1.0f / 1024.0f) + 1e-6f);
; }
; template <class Epi, class Sched, bool ALIGN_EPI = false, bool SP2 = false>
; __device__ __forceinline__ void gemm_phase(PG8_LAS unsigned char* lds, const Gemm g, const Sched& S, const Epi& E) {
;     const int tid = threadIdx.x, wid = __builtin_amdgcn_readfirstlane(tid >> 6), lane = tid & 63, wr = wid >> 2, wc = wid & 3, fr = lane & 15, fq = lane >> 4;
;     const int K = g.K, nt = K / BK;
;     unsigned voffA[2], voffB[2];
; #pragma unroll
;     for (int i = 0; i < 2; ++i) { int R, C; stage_rc(tid * 16 + i * 8192, R, C); const int Rb = Epi::PERM ? ((R & ~31) + perm32(R & 31)) : R;
;         voffA[i] = (unsigned)(R * K + C) * 2u; voffB[i] = (unsigned)(Rb * K + C) * 2u; }
;     const size_t kstep = (size_t)(BK * 2);
;     const size_t hstep = (size_t)HALF * K * 2;
;     const size_t tstep = 2 * hstep;
;     const unsigned ldsw = (unsigned)wid * 1024u;
;     const int aoff = lds_byte(wr * 64 + fr, fq * 8), boff = lds_byte(wc * 32 + fr, fq * 8);
;     ...
;     Unit cur, nxt; int ui = 0;
;     if (!S.next(0, cur)) return;
;     f32x4 acc[2][2][4][2];
; #pragma unroll
;     for (int a = 0; a < 2; ++a)
; #pragma unroll
;         for (int b = 0; b < 2; ++b)
; #pragma unroll
;             for (int m = 0; m < 4; ++m)
; #pragma unroll
;                 for (int n = 0; n < 2; ++n) acc[a][b][m][n] = (f32x4){0.f, 0.f, 0.f, 0.f};
;     bf16x8 At[4][2], B0[2][2], B1[2][2];
;     const char* cA = (const char*)g.A + (size_t)cur.pm * tstep; const char* cB = (const char*)g.Bt + (size_t)cur.pn * tstep;
;     S.a_ready(cur);
;     if constexpr (SP2) {
;         PG8_STAGE(PG8_SB(0, 0), cB, voffB); PG8_STAGE(PG8_SB(0, 1), cB + hstep, voffB); PG8_STAGE(PG8_SA(0, 0), cA, voffA); PG8_STAGE(PG8_SA(0, 1), cA + hstep, voffA);
;         if (wr == 1) PG8_BAR;
;         PG8_WAIT_V(2); PG8_BAR;
;         PG8_STAGE(PG8_SB(1, 0), cB + kstep, voffB); PG8_STAGE(PG8_SA(1, 0), cA + kstep, voffA); PG8_STAGE(PG8_SB(1, 1), cB + hstep + kstep, voffB);
;         PG8_WAIT_V(6); PG8_BAR;
.LBB0_1311:
	s_and_b64 vcc, exec, s[48:49]
	v_readfirstlane_b32 s8, v152
	s_waitcnt lgkmcnt(0)
	s_cbranch_vccnz .LBB0_1313
	s_ashr_i32 s0, s86, 31
	s_lshr_b32 s0, s0, 29
	s_add_i32 s0, s86, s0
	s_ashr_i32 s1, s0, 3
	s_and_b32 s0, s0, -8
	s_sub_i32 s0, s86, s0
	s_cmp_lt_i32 s0, 0
	s_movk_i32 s3, 0xb1
	s_cselect_b32 s3, s3, 0xb0
	s_mul_i32 s0, s0, s3
	s_add_i32 s0, s0, s1
	s_mul_hi_i32 s1, s0, 0x2e8ba2e9
	s_lshr_b32 s3, s1, 31
	s_ashr_i32 s1, s1, 5
	s_add_i32 s1, s1, s3
	s_lshl_b32 s3, s1, 3
	s_mulk_i32 s1, 0xb0
	s_sub_i32 s0, s0, s1
	s_sext_i32_i16 s1, s0
	s_bfe_u32 s1, s1, 0x3001c
	s_add_i32 s1, s0, s1
	s_sext_i32_i16 s4, s1
	s_and_b32 s1, s1, 0xfff8
	s_sub_i32 s0, s0, s1
	s_sext_i32_i16 s0, s0
	s_add_i32 s0, s3, s0
	s_ashr_i32 s10, s4, 3
.LBB0_1313:
	s_and_b64 vcc, exec, s[48:49]
	s_cbranch_vccz .Lhasunit_p8
	s_barrier
	s_branch .LBB0_1361
.Lhasunit_p8:
	s_lshr_b32 s6, s8, 6
	s_lshr_b32 s9, s8, 8
	s_lshl_b32 s3, s6, 10
	s_add_u32 s30, s72, 0x1700000
	s_addc_u32 s31, s73, 0
	s_ashr_i32 s1, s0, 31
	s_ashr_i32 s11, s10, 31
	s_lshl_b64 s[4:5], s[0:1], 19
	s_lshl_b64 s[14:15], s[10:11], 19
	s_add_u32 s26, s30, s14
	s_addc_u32 s27, s31, s15
	s_add_i32 s33, s3, 0
	s_add_i32 m0, s33, 0x10000
	v_mov_b32_e32 v159, 0
	s_barrier
	global_load_lds_dwordx4 v158, s[26:27]
	s_add_i32 m0, s33, 0x12000
	s_add_u32 s14, s26, 0x40000
	global_load_lds_dwordx4 v162, s[26:27]
	s_addc_u32 s15, s27, 0
	s_add_i32 m0, s33, 0x14000
	v_mov_b32_e32 v163, v159
	global_load_lds_dwordx4 v158, s[14:15]
	s_add_i32 m0, s33, 0x16000
	s_add_u32 s24, s76, s4
	s_addc_u32 s25, s77, s5
	s_add_i32 s34, s33, 0x2000
	global_load_lds_dwordx4 v162, s[14:15]
	s_mov_b32 m0, s33
	s_add_u32 s4, s24, 0x40000
	global_load_lds_dwordx4 v156, s[24:25]
	s_mov_b32 m0, s34
	s_addc_u32 s5, s25, 0
	s_add_i32 s35, s33, 0x4000
	global_load_lds_dwordx4 v160, s[24:25]
	s_mov_b32 m0, s35
	s_add_i32 s36, s33, 0x6000
	global_load_lds_dwordx4 v156, s[4:5]
	s_mov_b32 m0, s36
	v_mov_b32_e32 v157, v159
	global_load_lds_dwordx4 v160, s[4:5]
	s_movk_i32 s98, 0x100
	v_cmp_gt_u32_e32 vcc, s98, v152
	s_and_saveexec_b64 s[100:101], vcc
	s_cbranch_execz .Lrtab_p8
	s_waitcnt vmcnt(15)
	v_lshl_or_b32 v188, s0, 8, v152
	v_ashrrev_i32_e32 v189, 31, v188
	v_lshlrev_b64 v[188:189], 6, v[188:189]
	s_waitcnt vmcnt(10)
	v_lshl_add_u64 v[204:205], s[12:13], 0, v[188:189]
	global_load_dwordx4 v[188:191], v[204:205], off
	global_load_dwordx4 v[192:195], v[204:205], off offset:32
	global_load_dwordx4 v[196:199], v[204:205], off offset:16
	global_load_dwordx4 v[200:203], v[204:205], off offset:48
	v_mov_b32_e32 v206, 0x358637bd
	s_mov_b32 s98, 0xf800000
	s_waitcnt vmcnt(3)
	v_mov_b32_e32 v204, v188
	s_waitcnt vmcnt(2)
	v_mov_b32_e32 v205, v192
	v_mov_b32_e32 v192, v189
	v_mov_b32_e32 v188, v190
	v_mov_b32_e32 v189, v194
	v_mov_b32_e32 v194, v191
	s_waitcnt vmcnt(1)
	v_mov_b32_e32 v190, v196
	s_waitcnt vmcnt(0)
	v_mov_b32_e32 v191, v200
	v_mov_b32_e32 v200, v197
	v_mov_b32_e32 v196, v198
	v_mov_b32_e32 v197, v202
	v_mov_b32_e32 v202, v199
	v_pk_add_f32 v[192:193], v[204:205], v[192:193]
	v_pk_add_f32 v[188:189], v[188:189], v[194:195]
	v_pk_add_f32 v[190:191], v[190:191], v[200:201]
	v_pk_add_f32 v[194:195], v[196:197], v[202:203]
	v_pk_add_f32 v[188:189], v[192:193], v[188:189]
	v_pk_add_f32 v[190:191], v[190:191], v[194:195]
	s_nop 0
	v_pk_add_f32 v[188:189], v[188:189], v[190:191]
	v_mov_b32_e32 v190, 0x260
	v_add_f32_e32 v188, v188, v189
	v_fmac_f32_e32 v206, 0x3a800000, v188
	v_mul_f32_e32 v188, 0x4f800000, v206
	v_cmp_gt_f32_e32 vcc, s98, v206
	s_nop 1
	v_cndmask_b32_e32 v188, v206, v188, vcc
	v_sqrt_f32_e32 v189, v188
	s_nop 0
	v_add_u32_e32 v191, -1, v189
	v_add_u32_e32 v192, 1, v189
	v_fma_f32 v193, -v191, v189, v188
	v_fma_f32 v194, -v192, v189, v188
	v_cmp_ge_f32_e64 s[98:99], 0, v193
	s_nop 1
	v_cndmask_b32_e64 v189, v189, v191, s[98:99]
	v_cmp_lt_f32_e64 s[98:99], 0, v194
	s_nop 1
	v_cndmask_b32_e64 v189, v189, v192, s[98:99]
	v_mul_f32_e32 v191, 0x37800000, v189
	v_cndmask_b32_e32 v189, v189, v191, vcc
	v_cmp_class_f32_e32 vcc, v188, v190
	v_lshl_add_u32 v191, v152, 2, 0
	s_nop 0
	v_cndmask_b32_e32 v188, v189, v188, vcc
	v_div_scale_f32 v189, s[98:99], v188, v188, 1.0
	v_rcp_f32_e32 v190, v189
	v_div_scale_f32 v192, vcc, 1.0, v188, 1.0
	v_fma_f32 v193, -v189, v190, 1.0
	v_fmac_f32_e32 v190, v193, v190
	v_mul_f32_e32 v193, v192, v190
	v_fma_f32 v194, -v189, v193, v192
	v_fmac_f32_e32 v193, v194, v190
	v_fma_f32 v189, -v189, v193, v192
	v_div_fmas_f32 v189, v189, v190, v193
	v_div_fixup_f32 v188, v189, v188, 1.0
	v_add_u32_e32 v189, 0x20100, v191
	ds_write_b32 v189, v188

;     __host__ __device__ bool next(int i, Unit& u) const {
;         const long L = (long)i * G + c; if (L >= nwg) return false;
;         int wgid = (int)L; { const int q = nwg / NXCD, r = nwg % NXCD, xcd = wgid % NXCD, off = wgid / NXCD; wgid = (xcd < r ? xcd * (q + 1) : r * (q + 1) + (xcd - r) * q) + off; }
;         const int nig = WGM * nN, gid = wgid / nig, fm = gid * WGM, gsz = (nM - fm) < WGM ? (nM - fm) : WGM;
;         u.pm = fm + ((wgid % nig) % gsz); u.pn = (wgid % nig) / gsz; return true;
; __global__ void __launch_bounds__(512, 2) fwd_megakernel(Params p) {
;     ...
;     { pg8::Gemm g{HB, (const bf16*)(ws + WS_WD2), S, DM, DFF}; pg8::StaticOrder so; so.init(S, DM, G, (int)blockIdx.x);
;       pg8::EpiFinal E{XB, p.out, SS3, (unsigned*)(ws + WS_PCNT), p.nf, 0.5f}; pg8::gemm_phase<pg8::EpiFinal, pg8::StaticOrder, true, true>(ldsl, g, so, E); }
.Lgb_done_8:
.LBB0_1419:
	s_or_b64 exec, exec, s[0:1]
	v_readlane_b32 s0, v255, 12
	v_readlane_b32 s1, v255, 13
	s_and_b64 vcc, exec, s[0:1]
	v_readfirstlane_b32 s4, v152
	s_waitcnt lgkmcnt(0)
	s_cbranch_vccnz .LBB0_1425
	s_ashr_i32 s0, s86, 31
	s_lshr_b32 s0, s0, 29
	s_add_i32 s5, s86, s0
	s_and_b32 s0, s5, -8
	s_sub_i32 s2, s86, s0
	s_cmp_gt_i32 s2, -1
	s_cbranch_scc0 .LBB0_1422
	s_lshl_b32 s3, s2, 5
	s_ashr_i32 s0, s5, 3
	s_cbranch_execz .LBB0_1423
	s_branch .LBB0_1424

; #define PG8_STAGE(bufoff, gbase, voff) do { _Pragma("unroll") for (int _i = 0; _i < 2; ++_i) \
;         __builtin_amdgcn_global_load_lds((const unsigned*)((const char*)(gbase) + (voff)[_i]), (PG8_LAS unsigned*)(lds + (bufoff) + ldsw + _i * 8192), 16, 0, 0); } while (0)
; #define PG8_WAIT_V(n) asm volatile("s_waitcnt vmcnt(" #n ")" ::: "memory")
; #define PG8_BAR __builtin_amdgcn_s_barrier()
; template <class Epi, class Sched, bool ALIGN_EPI = false, bool SP2 = false>
; __device__ __forceinline__ void gemm_phase(PG8_LAS unsigned char* lds, const Gemm g, const Sched& S, const Epi& E) {
;     ...
;     for (int i = 0; i < 2; ++i) { int R, C; stage_rc(tid * 16 + i * 8192, R, C); const int Rb = Epi::PERM ? ((R & ~31) + perm32(R & 31)) : R;
;         voffA[i] = (unsigned)(R * K + C) * 2u; voffB[i] = (unsigned)(Rb * K + C) * 2u; }
;     const size_t kstep = (size_t)(BK * 2);
;     const size_t hstep = (size_t)HALF * K * 2;
;     const size_t tstep = 2 * hstep;
;     const unsigned ldsw = (unsigned)wid * 1024u;
;     const int aoff = lds_byte(wr * 64 + fr, fq * 8), boff = lds_byte(wc * 32 + fr, fq * 8);
;     ...
;     Unit cur, nxt; int ui = 0;
;     if (!S.next(0, cur)) return;
;     f32x4 acc[2][2][4][2];
; #pragma unroll
;     for (int a = 0; a < 2; ++a)
; #pragma unroll
;         for (int b = 0; b < 2; ++b)
; #pragma unroll
;             for (int m = 0; m < 4; ++m)
; #pragma unroll
;                 for (int n = 0; n < 2; ++n) acc[a][b][m][n] = (f32x4){0.f, 0.f, 0.f, 0.f};
;     bf16x8 At[4][2], B0[2][2], B1[2][2];
;     const char* cA = (const char*)g.A + (size_t)cur.pm * tstep; const char* cB = (const char*)g.Bt + (size_t)cur.pn * tstep;
;     S.a_ready(cur);
;     if constexpr (SP2) {
;         PG8_STAGE(PG8_SB(0, 0), cB, voffB); PG8_STAGE(PG8_SB(0, 1), cB + hstep, voffB); PG8_STAGE(PG8_SA(0, 0), cA, voffA); PG8_STAGE(PG8_SA(0, 1), cA + hstep, voffA);
;         if (wr == 1) PG8_BAR;
;         PG8_WAIT_V(2); PG8_BAR;
;         PG8_STAGE(PG8_SB(1, 0), cB + kstep, voffB); PG8_STAGE(PG8_SA(1, 0), cA + kstep, voffA); PG8_STAGE(PG8_SB(1, 1), cB + hstep + kstep, voffB);
;         PG8_WAIT_V(6); PG8_BAR;
.LBB0_1425:
	v_readlane_b32 s0, v255, 12
	v_readlane_b32 s1, v255, 13
	s_and_b64 vcc, exec, s[0:1]
	s_cbranch_vccz .Lhasunit_p9
	s_barrier
	s_branch .LBB0_1472
.Lhasunit_p9:
	s_add_u32 s2, s72, 0x2200000
	s_addc_u32 s3, s73, 0
	s_lshr_b32 s1, s4, 6
	s_lshr_b32 s0, s4, 8
	s_lshl_b32 s28, s1, 10
	s_mul_i32 s7, s12, 0x160000
	s_mul_hi_i32 s6, s12, 0x160000
	s_add_u32 s10, s2, s7
	s_addc_u32 s11, s3, s6
	s_add_i32 s29, s28, 0
	s_add_i32 m0, s29, 0x10000
	s_mul_i32 s8, s47, 0x160000
	s_barrier
	global_load_lds_dwordx4 v166, s[10:11]
	s_add_i32 m0, s29, 0x12000
	s_add_u32 s6, s10, 0xb0000
	global_load_lds_dwordx4 v170, s[10:11]
	s_addc_u32 s7, s11, 0
	s_add_i32 m0, s29, 0x14000
	s_mul_hi_i32 s5, s47, 0x160000
	global_load_lds_dwordx4 v166, s[6:7]
	s_add_i32 m0, s29, 0x16000
	s_add_u32 s26, s78, s8
	s_addc_u32 s27, s79, s5
	s_add_i32 s30, s29, 0x2000
	global_load_lds_dwordx4 v170, s[6:7]
	s_mov_b32 m0, s29
	s_add_u32 s6, s26, 0xb0000
	global_load_lds_dwordx4 v164, s[26:27]
	s_mov_b32 m0, s30
	s_addc_u32 s7, s27, 0
	s_add_i32 s31, s29, 0x4000
	global_load_lds_dwordx4 v168, s[26:27]
	s_mov_b32 m0, s31
	s_add_i32 s33, s29, 0x6000
	global_load_lds_dwordx4 v164, s[6:7]
	s_mov_b32 m0, s33
	v_mov_b32_e32 v167, 0
	global_load_lds_dwordx4 v168, s[6:7]
	v_mov_b32_e32 v171, v167
	v_mov_b32_e32 v165, v167
	v_mov_b32_e32 v169, v167
	s_cmp_eq_u32 s0, 1
	s_mov_b32 s13, 0
	v_lshl_add_u64 v[6:7], s[10:11], 0, v[166:167]
	v_lshl_add_u64 v[4:5], s[10:11], 0, v[170:171]
	v_lshl_add_u64 v[0:1], s[26:27], 0, v[164:165]
	s_cselect_b64 s[14:15], -1, 0
	s_cmp_lg_u32 s0, 1
	v_lshl_add_u64 v[2:3], s[26:27], 0, v[168:169]
	s_cbranch_scc1 .LBB0_1428
	s_barrier
